# grid barrier: the first workgroup of an XCD to arrive starts an L2 write-back while it waits, so the last arriver's write-back has less left (on top of flat release)
# baseline (speedup 1.0000x reference)
; __device__ __forceinline__ unsigned xb_ld(unsigned* p)              { return __hip_atomic_load(p, __ATOMIC_RELAXED, __HIP_MEMORY_SCOPE_AGENT); }
; __device__ __forceinline__ unsigned xb_add(unsigned* p, unsigned v) { return __hip_atomic_fetch_add(p, v, __ATOMIC_RELAXED, __HIP_MEMORY_SCOPE_AGENT); }
; #define XB_SPIN(cond, bar) do { unsigned _sp = 0; while (cond) { __builtin_amdgcn_s_sleep(1); \
;     if ((++_sp & 255u) == 0u) { if (xb_ld(&(bar)[XB_TMO])) break; if (_sp > XB_SPIN_CAP) { atomicAdd(&(bar)[XB_TMO], 1u); break; } } } } while (0)
; __device__ __forceinline__ void xcd_barrier(const XcdBarrier& b) {
;     ...
;         const unsigned old = xb_add(&bar[XB_XSUB(b.x)], 1u);
;         const unsigned gen = old / nloc;
;         if (old + 1u == (gen + 1u) * nloc) {
;             __builtin_amdgcn_fence(__ATOMIC_RELEASE, "agent");
;             asm volatile("s_waitcnt vmcnt(0)" ::: "memory");
;             const unsigned og = xb_add(&bar[XB_TOP], 1u);
;             const unsigned tg = og / nx;
;             if (og + 1u == (tg + 1u) * nx) xb_add(&bar[XB_TOPGEN], 1u);
;             else XB_SPIN(xb_ld(&bar[XB_TOPGEN]) == tg, bar);
;             __builtin_amdgcn_fence(__ATOMIC_ACQUIRE, "agent");
;             xb_add(&bar[XB_XGEN(b.x)], 1u);
;             asm volatile("s_waitcnt vmcnt(0)" ::: "memory");
;         } else {
;             XB_SPIN(xb_ld(&bar[XB_XGEN(b.x)]) == gen, bar);
.LBB0_122:
	s_or_b64 exec, exec, s[12:13]
	v_cvt_f32_u32_e32 v4, v2
	s_waitcnt vmcnt(0)
	v_readfirstlane_b32 s3, v3
	v_sub_u32_e32 v3, 0, v2
	v_rcp_iflag_f32_e32 v4, v4
	v_add_u32_e32 v5, s3, v1
	v_mul_f32_e32 v4, 0x4f7ffffe, v4
	v_cvt_u32_f32_e32 v4, v4
	v_mul_lo_u32 v1, v3, v4
	v_mul_hi_u32 v1, v4, v1
	v_add_u32_e32 v1, v4, v1
	v_mul_hi_u32 v1, v5, v1
	v_mul_lo_u32 v3, v1, v2
	v_sub_u32_e32 v3, v5, v3
	v_add_u32_e32 v4, 1, v1
	v_cmp_ge_u32_e32 vcc, v3, v2
	s_nop 1
	v_cndmask_b32_e32 v1, v1, v4, vcc
	v_sub_u32_e32 v4, v3, v2
	v_cndmask_b32_e32 v3, v3, v4, vcc
	v_add_u32_e32 v4, 1, v1
	v_cmp_ge_u32_e32 vcc, v3, v2
	v_add_u32_e32 v3, 1, v5
	s_nop 0
	v_cndmask_b32_e32 v1, v1, v4, vcc
	v_mul_lo_u32 v4, v2, v1
	v_add_u32_e32 v2, v4, v2
	v_cmp_ne_u32_e32 vcc, v3, v2
	s_and_saveexec_b64 s[10:11], vcc
	s_xor_b64 s[10:11], exec, s[10:11]
	s_cbranch_execz .LBB0_136
	s_waitcnt lgkmcnt(0)
	v_cmp_ne_u32_e32 vcc, v5, v4
	s_cbranch_vccnz .Lbw_skip_0
	buffer_wbl2 sc1
.Lbw_skip_0:
	v_mov_b32_e32 v0, 0xcb500
	global_load_dword v0, v0, s[6:7] sc1
	s_add_u32 s16, s6, 0xcb500
	s_addc_u32 s17, s7, 0
	s_waitcnt vmcnt(0)
	v_cmp_eq_u32_e32 vcc, v0, v1
	s_and_saveexec_b64 s[12:13], vcc
	s_cbranch_execz .LBB0_135
	s_add_u32 s14, s6, 0xc8200
	s_addc_u32 s15, s7, 0
	s_mov_b32 s3, 1
	s_mov_b64 s[18:19], 0
	v_mov_b32_e32 v0, 0
	s_branch .LBB0_126

; __device__ __forceinline__ unsigned xb_ld(unsigned* p)              { return __hip_atomic_load(p, __ATOMIC_RELAXED, __HIP_MEMORY_SCOPE_AGENT); }
; #define XB_SPIN(cond, bar) do { unsigned _sp = 0; while (cond) { __builtin_amdgcn_s_sleep(1); \
;     if ((++_sp & 255u) == 0u) { if (xb_ld(&(bar)[XB_TMO])) break; if (_sp > XB_SPIN_CAP) { atomicAdd(&(bar)[XB_TMO], 1u); break; } } } } while (0)
; __device__ __forceinline__ void xcd_barrier(const XcdBarrier& b) {
;     ...
;         } else {
;             XB_SPIN(xb_ld(&bar[XB_XGEN(b.x)]) == gen, bar);
.Lbw_skip_2:
	v_mov_b32_e32 v0, 0xcb500
	global_load_dword v0, v0, s[6:7] sc1
	s_add_u32 s18, s6, 0xcb500
	s_addc_u32 s19, s7, 0
	s_waitcnt vmcnt(0)
	v_cmp_eq_u32_e32 vcc, v0, v1
	s_and_saveexec_b64 s[12:13], vcc
	s_cbranch_execz .LBB0_270
	s_add_u32 s14, s6, 0xc8200
	s_addc_u32 s15, s7, 0
	s_mov_b32 s3, 1
	s_mov_b64 s[20:21], 0
	v_mov_b32_e32 v0, 0
	s_branch .LBB0_261

; __device__ __forceinline__ unsigned xb_ld(unsigned* p)              { return __hip_atomic_load(p, __ATOMIC_RELAXED, __HIP_MEMORY_SCOPE_AGENT); }
; #define XB_SPIN(cond, bar) do { unsigned _sp = 0; while (cond) { __builtin_amdgcn_s_sleep(1); \
;     if ((++_sp & 255u) == 0u) { if (xb_ld(&(bar)[XB_TMO])) break; if (_sp > XB_SPIN_CAP) { atomicAdd(&(bar)[XB_TMO], 1u); break; } } } } while (0)
; __device__ __forceinline__ void xcd_barrier(const XcdBarrier& b) {
;     ...
;         } else {
;             XB_SPIN(xb_ld(&bar[XB_XGEN(b.x)]) == gen, bar);
.Lbw_skip_3:
	v_mov_b32_e32 v0, 0xcb500
	global_load_dword v0, v0, s[6:7] sc1
	s_add_u32 s20, s6, 0xcb500
	s_addc_u32 s21, s7, 0
	s_waitcnt vmcnt(0)
	v_cmp_eq_u32_e32 vcc, v0, v1
	s_and_saveexec_b64 s[12:13], vcc
	s_cbranch_execz .LBB0_414
	s_add_u32 s14, s6, 0xc8200
	s_addc_u32 s15, s7, 0
	s_mov_b32 s3, 1
	s_mov_b64 s[22:23], 0
	v_mov_b32_e32 v0, 0
	s_branch .LBB0_405

; __device__ __forceinline__ unsigned xb_ld(unsigned* p)              { return __hip_atomic_load(p, __ATOMIC_RELAXED, __HIP_MEMORY_SCOPE_AGENT); }
; __device__ __forceinline__ unsigned xb_add(unsigned* p, unsigned v) { return __hip_atomic_fetch_add(p, v, __ATOMIC_RELAXED, __HIP_MEMORY_SCOPE_AGENT); }
; #define XB_SPIN(cond, bar) do { unsigned _sp = 0; while (cond) { __builtin_amdgcn_s_sleep(1); \
;     if ((++_sp & 255u) == 0u) { if (xb_ld(&(bar)[XB_TMO])) break; if (_sp > XB_SPIN_CAP) { atomicAdd(&(bar)[XB_TMO], 1u); break; } } } } while (0)
; __device__ __forceinline__ void xcd_barrier(const XcdBarrier& b) {
;     ...
;         const unsigned old = xb_add(&bar[XB_XSUB(b.x)], 1u);
;         const unsigned gen = old / nloc;
;         if (old + 1u == (gen + 1u) * nloc) {
;             __builtin_amdgcn_fence(__ATOMIC_RELEASE, "agent");
;             asm volatile("s_waitcnt vmcnt(0)" ::: "memory");
;             const unsigned og = xb_add(&bar[XB_TOP], 1u);
;             const unsigned tg = og / nx;
;             if (og + 1u == (tg + 1u) * nx) xb_add(&bar[XB_TOPGEN], 1u);
;             else XB_SPIN(xb_ld(&bar[XB_TOPGEN]) == tg, bar);
;             __builtin_amdgcn_fence(__ATOMIC_ACQUIRE, "agent");
;             xb_add(&bar[XB_XGEN(b.x)], 1u);
;             asm volatile("s_waitcnt vmcnt(0)" ::: "memory");
;         } else {
;             XB_SPIN(xb_ld(&bar[XB_XGEN(b.x)]) == gen, bar);
.LBB0_865:
	s_or_b64 exec, exec, s[14:15]
	v_cvt_f32_u32_e32 v4, v2
	s_waitcnt vmcnt(0)
	v_readfirstlane_b32 s3, v3
	v_sub_u32_e32 v3, 0, v2
	v_rcp_iflag_f32_e32 v4, v4
	v_add_u32_e32 v5, s3, v1
	v_mul_f32_e32 v4, 0x4f7ffffe, v4
	v_cvt_u32_f32_e32 v4, v4
	v_mul_lo_u32 v1, v3, v4
	v_mul_hi_u32 v1, v4, v1
	v_add_u32_e32 v1, v4, v1
	v_mul_hi_u32 v1, v5, v1
	v_mul_lo_u32 v3, v1, v2
	v_sub_u32_e32 v3, v5, v3
	v_add_u32_e32 v4, 1, v1
	v_cmp_ge_u32_e32 vcc, v3, v2
	s_nop 1
	v_cndmask_b32_e32 v1, v1, v4, vcc
	v_sub_u32_e32 v4, v3, v2
	v_cndmask_b32_e32 v3, v3, v4, vcc
	v_add_u32_e32 v4, 1, v1
	v_cmp_ge_u32_e32 vcc, v3, v2
	v_add_u32_e32 v3, 1, v5
	s_nop 0
	v_cndmask_b32_e32 v1, v1, v4, vcc
	v_mul_lo_u32 v4, v2, v1
	v_add_u32_e32 v2, v4, v2
	v_cmp_ne_u32_e32 vcc, v3, v2
	s_and_saveexec_b64 s[6:7], vcc
	s_xor_b64 s[12:13], exec, s[6:7]
	s_cbranch_execz .LBB0_879
	s_waitcnt lgkmcnt(0)
	v_cmp_ne_u32_e32 vcc, v5, v4
	s_cbranch_vccnz .Lbw_skip_4
	buffer_wbl2 sc1
.Lbw_skip_4:
	v_mov_b32_e32 v0, 0xcb500
	global_load_dword v0, v0, s[8:9] sc1
	s_add_u32 s22, s8, 0xcb500
	s_addc_u32 s23, s9, 0
	s_waitcnt vmcnt(0)
	v_cmp_eq_u32_e32 vcc, v0, v1
	s_and_saveexec_b64 s[14:15], vcc
	s_cbranch_execz .LBB0_878
	s_add_u32 s20, s8, 0xc8200
	s_addc_u32 s21, s9, 0
	s_mov_b32 s3, 1
	s_mov_b64 s[26:27], 0
	v_mov_b32_e32 v0, 0
	s_branch .LBB0_869

; __device__ __forceinline__ unsigned xb_ld(unsigned* p)              { return __hip_atomic_load(p, __ATOMIC_RELAXED, __HIP_MEMORY_SCOPE_AGENT); }
; __device__ __forceinline__ unsigned xb_add(unsigned* p, unsigned v) { return __hip_atomic_fetch_add(p, v, __ATOMIC_RELAXED, __HIP_MEMORY_SCOPE_AGENT); }
; #define XB_SPIN(cond, bar) do { unsigned _sp = 0; while (cond) { __builtin_amdgcn_s_sleep(1); \
;     if ((++_sp & 255u) == 0u) { if (xb_ld(&(bar)[XB_TMO])) break; if (_sp > XB_SPIN_CAP) { atomicAdd(&(bar)[XB_TMO], 1u); break; } } } } while (0)
; __device__ __forceinline__ void xcd_barrier(const XcdBarrier& b) {
;     ...
;         const unsigned old = xb_add(&bar[XB_XSUB(b.x)], 1u);
;         const unsigned gen = old / nloc;
;         if (old + 1u == (gen + 1u) * nloc) {
;             __builtin_amdgcn_fence(__ATOMIC_RELEASE, "agent");
;             asm volatile("s_waitcnt vmcnt(0)" ::: "memory");
;             const unsigned og = xb_add(&bar[XB_TOP], 1u);
;             const unsigned tg = og / nx;
;             if (og + 1u == (tg + 1u) * nx) xb_add(&bar[XB_TOPGEN], 1u);
;             else XB_SPIN(xb_ld(&bar[XB_TOPGEN]) == tg, bar);
;             __builtin_amdgcn_fence(__ATOMIC_ACQUIRE, "agent");
;             xb_add(&bar[XB_XGEN(b.x)], 1u);
;             asm volatile("s_waitcnt vmcnt(0)" ::: "memory");
;         } else {
;             XB_SPIN(xb_ld(&bar[XB_XGEN(b.x)]) == gen, bar);
.LBB0_1006:
	s_or_b64 exec, exec, s[20:21]
	v_cvt_f32_u32_e32 v4, v2
	s_waitcnt vmcnt(0)
	v_readfirstlane_b32 s6, v3
	v_sub_u32_e32 v3, 0, v2
	v_rcp_iflag_f32_e32 v4, v4
	v_add_u32_e32 v5, s6, v1
	v_mul_f32_e32 v4, 0x4f7ffffe, v4
	v_cvt_u32_f32_e32 v4, v4
	v_mul_lo_u32 v1, v3, v4
	v_mul_hi_u32 v1, v4, v1
	v_add_u32_e32 v1, v4, v1
	v_mul_hi_u32 v1, v5, v1
	v_mul_lo_u32 v3, v1, v2
	v_sub_u32_e32 v3, v5, v3
	v_add_u32_e32 v4, 1, v1
	v_cmp_ge_u32_e32 vcc, v3, v2
	s_nop 1
	v_cndmask_b32_e32 v1, v1, v4, vcc
	v_sub_u32_e32 v4, v3, v2
	v_cndmask_b32_e32 v3, v3, v4, vcc
	v_add_u32_e32 v4, 1, v1
	v_cmp_ge_u32_e32 vcc, v3, v2
	v_add_u32_e32 v3, 1, v5
	s_nop 0
	v_cndmask_b32_e32 v1, v1, v4, vcc
	v_mul_lo_u32 v4, v2, v1
	v_add_u32_e32 v2, v4, v2
	v_cmp_ne_u32_e32 vcc, v3, v2
	s_and_saveexec_b64 s[6:7], vcc
	s_xor_b64 s[14:15], exec, s[6:7]
	s_cbranch_execz .LBB0_1020
	s_waitcnt lgkmcnt(0)
	v_cmp_ne_u32_e32 vcc, v5, v4
	s_cbranch_vccnz .Lbw_skip_5
	buffer_wbl2 sc1
.Lbw_skip_5:
	v_mov_b32_e32 v0, 0xcb500
	global_load_dword v0, v0, s[10:11] sc1
	s_add_u32 s26, s10, 0xcb500
	s_addc_u32 s27, s11, 0
	s_waitcnt vmcnt(0)
	v_cmp_eq_u32_e32 vcc, v0, v1
	s_and_saveexec_b64 s[20:21], vcc
	s_cbranch_execz .LBB0_1019
	s_add_u32 s22, s10, 0xc8200
	s_addc_u32 s23, s11, 0
	s_mov_b32 s6, 1
	s_mov_b64 s[36:37], 0
	v_mov_b32_e32 v0, 0
	s_branch .LBB0_1010

; __device__ __forceinline__ unsigned xb_ld(unsigned* p)              { return __hip_atomic_load(p, __ATOMIC_RELAXED, __HIP_MEMORY_SCOPE_AGENT); }
; __device__ __forceinline__ unsigned xb_add(unsigned* p, unsigned v) { return __hip_atomic_fetch_add(p, v, __ATOMIC_RELAXED, __HIP_MEMORY_SCOPE_AGENT); }
; #define XB_SPIN(cond, bar) do { unsigned _sp = 0; while (cond) { __builtin_amdgcn_s_sleep(1); \
;     if ((++_sp & 255u) == 0u) { if (xb_ld(&(bar)[XB_TMO])) break; if (_sp > XB_SPIN_CAP) { atomicAdd(&(bar)[XB_TMO], 1u); break; } } } } while (0)
; __device__ __forceinline__ void xcd_barrier(const XcdBarrier& b) {
;     ...
;         const unsigned old = xb_add(&bar[XB_XSUB(b.x)], 1u);
;         const unsigned gen = old / nloc;
;         if (old + 1u == (gen + 1u) * nloc) {
;             __builtin_amdgcn_fence(__ATOMIC_RELEASE, "agent");
;             asm volatile("s_waitcnt vmcnt(0)" ::: "memory");
;             const unsigned og = xb_add(&bar[XB_TOP], 1u);
;             const unsigned tg = og / nx;
;             if (og + 1u == (tg + 1u) * nx) xb_add(&bar[XB_TOPGEN], 1u);
;             else XB_SPIN(xb_ld(&bar[XB_TOPGEN]) == tg, bar);
;             __builtin_amdgcn_fence(__ATOMIC_ACQUIRE, "agent");
;             xb_add(&bar[XB_XGEN(b.x)], 1u);
;             asm volatile("s_waitcnt vmcnt(0)" ::: "memory");
;         } else {
;             XB_SPIN(xb_ld(&bar[XB_XGEN(b.x)]) == gen, bar);
.LBB0_1212:
	s_or_b64 exec, exec, s[20:21]
	v_cvt_f32_u32_e32 v4, v2
	s_waitcnt vmcnt(0)
	v_readfirstlane_b32 s6, v3
	v_sub_u32_e32 v3, 0, v2
	v_rcp_iflag_f32_e32 v4, v4
	v_add_u32_e32 v5, s6, v1
	v_mul_f32_e32 v4, 0x4f7ffffe, v4
	v_cvt_u32_f32_e32 v4, v4
	v_mul_lo_u32 v1, v3, v4
	v_mul_hi_u32 v1, v4, v1
	v_add_u32_e32 v1, v4, v1
	v_mul_hi_u32 v1, v5, v1
	v_mul_lo_u32 v3, v1, v2
	v_sub_u32_e32 v3, v5, v3
	v_add_u32_e32 v4, 1, v1
	v_cmp_ge_u32_e32 vcc, v3, v2
	s_nop 1
	v_cndmask_b32_e32 v1, v1, v4, vcc
	v_sub_u32_e32 v4, v3, v2
	v_cndmask_b32_e32 v3, v3, v4, vcc
	v_add_u32_e32 v4, 1, v1
	v_cmp_ge_u32_e32 vcc, v3, v2
	v_add_u32_e32 v3, 1, v5
	s_nop 0
	v_cndmask_b32_e32 v1, v1, v4, vcc
	v_mul_lo_u32 v4, v2, v1
	v_add_u32_e32 v2, v4, v2
	v_cmp_ne_u32_e32 vcc, v3, v2
	s_and_saveexec_b64 s[6:7], vcc
	s_xor_b64 s[18:19], exec, s[6:7]
	s_cbranch_execz .LBB0_1226
	s_waitcnt lgkmcnt(0)
	v_cmp_ne_u32_e32 vcc, v5, v4
	s_cbranch_vccnz .Lbw_skip_7
	buffer_wbl2 sc1
.Lbw_skip_7:
	v_mov_b32_e32 v0, 0xcb500
	global_load_dword v0, v0, s[12:13] sc1
	s_add_u32 s26, s12, 0xcb500
	s_addc_u32 s27, s13, 0
	s_waitcnt vmcnt(0)
	v_cmp_eq_u32_e32 vcc, v0, v1
	s_and_saveexec_b64 s[20:21], vcc
	s_cbranch_execz .LBB0_1225
	s_add_u32 s22, s12, 0xc8200
	s_addc_u32 s23, s13, 0
	s_mov_b32 s6, 1
	s_mov_b64 s[36:37], 0
	v_mov_b32_e32 v0, 0
	s_branch .LBB0_1216

; __device__ __forceinline__ unsigned xb_ld(unsigned* p)              { return __hip_atomic_load(p, __ATOMIC_RELAXED, __HIP_MEMORY_SCOPE_AGENT); }
; #define XB_SPIN(cond, bar) do { unsigned _sp = 0; while (cond) { __builtin_amdgcn_s_sleep(1); \
;     if ((++_sp & 255u) == 0u) { if (xb_ld(&(bar)[XB_TMO])) break; if (_sp > XB_SPIN_CAP) { atomicAdd(&(bar)[XB_TMO], 1u); break; } } } } while (0)
; __device__ __forceinline__ void xcd_barrier(const XcdBarrier& b) {
;     ...
;         } else {
;             XB_SPIN(xb_ld(&bar[XB_XGEN(b.x)]) == gen, bar);
.Lbw_skip_8:
	v_mov_b32_e32 v0, 0xcb500
	global_load_dword v0, v0, s[14:15] sc1
	s_add_u32 s26, s14, 0xcb500
	s_addc_u32 s27, s15, 0
	s_waitcnt vmcnt(0)
	v_cmp_eq_u32_e32 vcc, v0, v1
	s_and_saveexec_b64 s[20:21], vcc
	s_cbranch_execz .LBB0_1301
	s_add_u32 s22, s14, 0xc8200
	s_addc_u32 s23, s15, 0
	s_mov_b32 s6, 1
	s_mov_b64 s[36:37], 0
	v_mov_b32_e32 v0, 0
	s_branch .LBB0_1292

; __device__ __forceinline__ unsigned xb_ld(unsigned* p)              { return __hip_atomic_load(p, __ATOMIC_RELAXED, __HIP_MEMORY_SCOPE_AGENT); }
; __device__ __forceinline__ unsigned xb_add(unsigned* p, unsigned v) { return __hip_atomic_fetch_add(p, v, __ATOMIC_RELAXED, __HIP_MEMORY_SCOPE_AGENT); }
; #define XB_SPIN(cond, bar) do { unsigned _sp = 0; while (cond) { __builtin_amdgcn_s_sleep(1); \
;     if ((++_sp & 255u) == 0u) { if (xb_ld(&(bar)[XB_TMO])) break; if (_sp > XB_SPIN_CAP) { atomicAdd(&(bar)[XB_TMO], 1u); break; } } } } while (0)
; __device__ __forceinline__ void xcd_barrier(const XcdBarrier& b) {
;     ...
;         const unsigned old = xb_add(&bar[XB_XSUB(b.x)], 1u);
;         const unsigned gen = old / nloc;
;         if (old + 1u == (gen + 1u) * nloc) {
;             __builtin_amdgcn_fence(__ATOMIC_RELEASE, "agent");
;             asm volatile("s_waitcnt vmcnt(0)" ::: "memory");
;             const unsigned og = xb_add(&bar[XB_TOP], 1u);
;             const unsigned tg = og / nx;
;             if (og + 1u == (tg + 1u) * nx) xb_add(&bar[XB_TOPGEN], 1u);
;             else XB_SPIN(xb_ld(&bar[XB_TOPGEN]) == tg, bar);
;             __builtin_amdgcn_fence(__ATOMIC_ACQUIRE, "agent");
;             xb_add(&bar[XB_XGEN(b.x)], 1u);
;             asm volatile("s_waitcnt vmcnt(0)" ::: "memory");
;         } else {
;             XB_SPIN(xb_ld(&bar[XB_XGEN(b.x)]) == gen, bar);
.LBB0_1508:
	s_or_b64 exec, exec, s[18:19]
	v_cvt_f32_u32_e32 v4, v2
	s_waitcnt vmcnt(0)
	v_readfirstlane_b32 s6, v3
	v_sub_u32_e32 v3, 0, v2
	v_rcp_iflag_f32_e32 v4, v4
	v_add_u32_e32 v5, s6, v1
	v_mul_f32_e32 v4, 0x4f7ffffe, v4
	v_cvt_u32_f32_e32 v4, v4
	v_mul_lo_u32 v1, v3, v4
	v_mul_hi_u32 v1, v4, v1
	v_add_u32_e32 v1, v4, v1
	v_mul_hi_u32 v1, v5, v1
	v_mul_lo_u32 v3, v1, v2
	v_sub_u32_e32 v3, v5, v3
	v_add_u32_e32 v4, 1, v1
	v_cmp_ge_u32_e32 vcc, v3, v2
	s_nop 1
	v_cndmask_b32_e32 v1, v1, v4, vcc
	v_sub_u32_e32 v4, v3, v2
	v_cndmask_b32_e32 v3, v3, v4, vcc
	v_add_u32_e32 v4, 1, v1
	v_cmp_ge_u32_e32 vcc, v3, v2
	v_add_u32_e32 v3, 1, v5
	s_nop 0
	v_cndmask_b32_e32 v1, v1, v4, vcc
	v_mul_lo_u32 v4, v2, v1
	v_add_u32_e32 v2, v4, v2
	v_cmp_ne_u32_e32 vcc, v3, v2
	s_and_saveexec_b64 s[6:7], vcc
	s_xor_b64 s[16:17], exec, s[6:7]
	s_cbranch_execz .LBB0_1522
	s_waitcnt lgkmcnt(0)
	v_cmp_ne_u32_e32 vcc, v5, v4
	s_cbranch_vccnz .Lbw_skip_10
	buffer_wbl2 sc1
.Lbw_skip_10:
	v_mov_b32_e32 v0, 0xcb500
	global_load_dword v0, v0, s[12:13] sc1
	s_add_u32 s22, s12, 0xcb500
	s_addc_u32 s23, s13, 0
	s_waitcnt vmcnt(0)
	v_cmp_eq_u32_e32 vcc, v0, v1
	s_and_saveexec_b64 s[18:19], vcc
	s_cbranch_execz .LBB0_1521
	s_add_u32 s20, s12, 0xc8200
	s_addc_u32 s21, s13, 0
	s_mov_b32 s6, 1
	s_mov_b64 s[26:27], 0
	v_mov_b32_e32 v0, 0
	s_branch .LBB0_1512

; __device__ __forceinline__ unsigned xb_ld(unsigned* p)              { return __hip_atomic_load(p, __ATOMIC_RELAXED, __HIP_MEMORY_SCOPE_AGENT); }
; __device__ __forceinline__ unsigned xb_add(unsigned* p, unsigned v) { return __hip_atomic_fetch_add(p, v, __ATOMIC_RELAXED, __HIP_MEMORY_SCOPE_AGENT); }
; #define XB_SPIN(cond, bar) do { unsigned _sp = 0; while (cond) { __builtin_amdgcn_s_sleep(1); \
;     if ((++_sp & 255u) == 0u) { if (xb_ld(&(bar)[XB_TMO])) break; if (_sp > XB_SPIN_CAP) { atomicAdd(&(bar)[XB_TMO], 1u); break; } } } } while (0)
; __device__ __forceinline__ void xcd_barrier(const XcdBarrier& b) {
;     ...
;         const unsigned old = xb_add(&bar[XB_XSUB(b.x)], 1u);
;         const unsigned gen = old / nloc;
;         if (old + 1u == (gen + 1u) * nloc) {
;             __builtin_amdgcn_fence(__ATOMIC_RELEASE, "agent");
;             asm volatile("s_waitcnt vmcnt(0)" ::: "memory");
;             const unsigned og = xb_add(&bar[XB_TOP], 1u);
;             const unsigned tg = og / nx;
;             if (og + 1u == (tg + 1u) * nx) xb_add(&bar[XB_TOPGEN], 1u);
;             else XB_SPIN(xb_ld(&bar[XB_TOPGEN]) == tg, bar);
;             __builtin_amdgcn_fence(__ATOMIC_ACQUIRE, "agent");
;             xb_add(&bar[XB_XGEN(b.x)], 1u);
;             asm volatile("s_waitcnt vmcnt(0)" ::: "memory");
;         } else {
;             XB_SPIN(xb_ld(&bar[XB_XGEN(b.x)]) == gen, bar);
.LBB0_2116:
	s_or_b64 exec, exec, s[16:17]
	v_cvt_f32_u32_e32 v4, v2
	s_waitcnt vmcnt(0)
	v_readfirstlane_b32 s8, v3
	v_sub_u32_e32 v3, 0, v2
	v_rcp_iflag_f32_e32 v4, v4
	v_add_u32_e32 v5, s8, v1
	v_mul_f32_e32 v4, 0x4f7ffffe, v4
	v_cvt_u32_f32_e32 v4, v4
	v_mul_lo_u32 v1, v3, v4
	v_mul_hi_u32 v1, v4, v1
	v_add_u32_e32 v1, v4, v1
	v_mul_hi_u32 v1, v5, v1
	v_mul_lo_u32 v3, v1, v2
	v_sub_u32_e32 v3, v5, v3
	v_add_u32_e32 v4, 1, v1
	v_cmp_ge_u32_e32 vcc, v3, v2
	s_nop 1
	v_cndmask_b32_e32 v1, v1, v4, vcc
	v_sub_u32_e32 v4, v3, v2
	v_cndmask_b32_e32 v3, v3, v4, vcc
	v_add_u32_e32 v4, 1, v1
	v_cmp_ge_u32_e32 vcc, v3, v2
	v_add_u32_e32 v3, 1, v5
	s_nop 0
	v_cndmask_b32_e32 v1, v1, v4, vcc
	v_mul_lo_u32 v4, v2, v1
	v_add_u32_e32 v2, v4, v2
	v_cmp_ne_u32_e32 vcc, v3, v2
	s_and_saveexec_b64 s[8:9], vcc
	s_xor_b64 s[14:15], exec, s[8:9]
	s_cbranch_execz .LBB0_2130
	s_waitcnt lgkmcnt(0)
	v_cmp_ne_u32_e32 vcc, v5, v4
	s_cbranch_vccnz .Lbw_skip_12
	buffer_wbl2 sc1
.Lbw_skip_12:
	v_mov_b32_e32 v0, 0xcb500
	global_load_dword v0, v0, s[10:11] sc1
	s_add_u32 s20, s10, 0xcb500
	s_addc_u32 s21, s11, 0
	s_waitcnt vmcnt(0)
	v_cmp_eq_u32_e32 vcc, v0, v1
	s_and_saveexec_b64 s[16:17], vcc
	s_cbranch_execz .LBB0_2129
	s_add_u32 s18, s10, 0xc8200
	s_addc_u32 s19, s11, 0
	s_mov_b32 s8, 1
	s_mov_b64 s[22:23], 0
	v_mov_b32_e32 v0, 0
	s_branch .LBB0_2120

; __device__ __forceinline__ unsigned xb_ld(unsigned* p)              { return __hip_atomic_load(p, __ATOMIC_RELAXED, __HIP_MEMORY_SCOPE_AGENT); }
; __device__ __forceinline__ unsigned xb_add(unsigned* p, unsigned v) { return __hip_atomic_fetch_add(p, v, __ATOMIC_RELAXED, __HIP_MEMORY_SCOPE_AGENT); }
; #define XB_SPIN(cond, bar) do { unsigned _sp = 0; while (cond) { __builtin_amdgcn_s_sleep(1); \
;     if ((++_sp & 255u) == 0u) { if (xb_ld(&(bar)[XB_TMO])) break; if (_sp > XB_SPIN_CAP) { atomicAdd(&(bar)[XB_TMO], 1u); break; } } } } while (0)
; __device__ __forceinline__ void xcd_barrier(const XcdBarrier& b) {
;     ...
;         const unsigned old = xb_add(&bar[XB_XSUB(b.x)], 1u);
;         const unsigned gen = old / nloc;
;         if (old + 1u == (gen + 1u) * nloc) {
;             __builtin_amdgcn_fence(__ATOMIC_RELEASE, "agent");
;             asm volatile("s_waitcnt vmcnt(0)" ::: "memory");
;             const unsigned og = xb_add(&bar[XB_TOP], 1u);
;             const unsigned tg = og / nx;
;             if (og + 1u == (tg + 1u) * nx) xb_add(&bar[XB_TOPGEN], 1u);
;             else XB_SPIN(xb_ld(&bar[XB_TOPGEN]) == tg, bar);
;             __builtin_amdgcn_fence(__ATOMIC_ACQUIRE, "agent");
;             xb_add(&bar[XB_XGEN(b.x)], 1u);
;             asm volatile("s_waitcnt vmcnt(0)" ::: "memory");
;         } else {
;             XB_SPIN(xb_ld(&bar[XB_XGEN(b.x)]) == gen, bar);
.LBB0_2217:
	s_or_b64 exec, exec, s[14:15]
	v_cvt_f32_u32_e32 v4, v2
	s_waitcnt vmcnt(0)
	v_readfirstlane_b32 s12, v3
	v_sub_u32_e32 v3, 0, v2
	v_rcp_iflag_f32_e32 v4, v4
	v_add_u32_e32 v5, s12, v1
	v_mul_f32_e32 v4, 0x4f7ffffe, v4
	v_cvt_u32_f32_e32 v4, v4
	v_mul_lo_u32 v1, v3, v4
	v_mul_hi_u32 v1, v4, v1
	v_add_u32_e32 v1, v4, v1
	v_mul_hi_u32 v1, v5, v1
	v_mul_lo_u32 v3, v1, v2
	v_sub_u32_e32 v3, v5, v3
	v_add_u32_e32 v4, 1, v1
	v_cmp_ge_u32_e32 vcc, v3, v2
	s_nop 1
	v_cndmask_b32_e32 v1, v1, v4, vcc
	v_sub_u32_e32 v4, v3, v2
	v_cndmask_b32_e32 v3, v3, v4, vcc
	v_add_u32_e32 v4, 1, v1
	v_cmp_ge_u32_e32 vcc, v3, v2
	v_add_u32_e32 v3, 1, v5
	s_nop 0
	v_cndmask_b32_e32 v1, v1, v4, vcc
	v_mul_lo_u32 v4, v2, v1
	v_add_u32_e32 v2, v4, v2
	v_cmp_ne_u32_e32 vcc, v3, v2
	s_and_saveexec_b64 s[12:13], vcc
	s_xor_b64 s[12:13], exec, s[12:13]
	s_cbranch_execz .LBB0_2231
	s_waitcnt lgkmcnt(0)
	v_cmp_ne_u32_e32 vcc, v5, v4
	s_cbranch_vccnz .Lbw_skip_13
	buffer_wbl2 sc1
.Lbw_skip_13:
	v_mov_b32_e32 v0, 0xcb500
	global_load_dword v0, v0, s[8:9] sc1
	s_add_u32 s18, s8, 0xcb500
	s_addc_u32 s19, s9, 0
	s_waitcnt vmcnt(0)
	v_cmp_eq_u32_e32 vcc, v0, v1
	s_and_saveexec_b64 s[14:15], vcc
	s_cbranch_execz .LBB0_2230
	s_add_u32 s16, s8, 0xc8200
	s_addc_u32 s17, s9, 0
	s_mov_b32 s29, 1
	s_mov_b64 s[20:21], 0
	v_mov_b32_e32 v0, 0
	s_branch .LBB0_2221
